# attention prologue: Q tile fetched as contiguous rows (4x fewer cache-line requests) and re-laid out per lane through a per-wave padded LDS staging tile
# speedup vs baseline: 1.0067x; 1.0067x over previous
.LBB0_146:
	s_or_b64 exec, exec, s[44:45]
	s_ashr_i32 s3, s4, 1
	s_andn2_b32 s3, s3, 31
	v_and_b32_e32 v47, 31, v40
	s_add_i32 s3, s3, s11
	v_or_b32_e32 v202, s3, v47
	v_ashrrev_i32_e32 v203, 31, v202
	v_lshl_add_u64 v[0:1], v[202:203], 2, s[20:21]
	global_load_dword v237, v[0:1], off sc1
	v_lshl_add_u64 v[0:1], s[36:37], 0, v[202:203]
	v_readlane_b32 s14, v253, 43
	v_lshlrev_b64 v[0:1], 11, v[0:1]
	v_readlane_b32 s15, v253, 44
	v_bfe_u32 v45, v40, 5, 1
	s_lshl_b32 s36, s5, 1
	v_lshl_add_u64 v[0:1], s[14:15], 0, v[0:1]
	v_lshl_add_u64 v[200:201], v[0:1], 0, s[36:37]
	v_lshlrev_b32_e32 v49, 4, v45
	v_lshrrev_b32_e32 v98, 3, v47
	v_lshl_add_u32 v98, v45, 2, v98
	v_sub_u32_e32 v99, v98, v47
	v_lshl_add_u32 v99, v99, 11, v200
	v_and_b32_e32 v100, 7, v47
	v_lshl_add_u32 v99, v100, 4, v99
	v_subrev_u32_e32 v99, s74, v99
	v_mul_u32_u24_e32 v101, 0x90, v98
	v_lshl_add_u32 v101, v100, 4, v101
	v_and_b32_e32 v100, 0x1c0, v40
	v_mul_u32_u24_e32 v100, 0x48, v100
	v_add_u32_e32 v100, 0x11800, v100
	v_add_u32_e32 v101, v101, v100
	v_mul_u32_u24_e32 v98, 0x90, v47
	v_add3_u32 v100, v100, v98, v49
	buffer_load_dwordx4 v[0:3], v99, s[76:79], 0 offen sc1
	v_add_u32_e32 v98, 0x4000, v99
	buffer_load_dwordx4 v[36:39], v98, s[76:79], 0 offen sc1
	v_add_u32_e32 v98, 0x8000, v99
	buffer_load_dwordx4 v[74:77], v98, s[76:79], 0 offen sc1
	v_add_u32_e32 v98, 0xc000, v99
	buffer_load_dwordx4 v[62:65], v98, s[76:79], 0 offen sc1
	v_and_b32_e32 v5, 64, v227
	v_xor_b32_e32 v4, 32, v227
	v_add_u32_e32 v51, 64, v5
	s_lshl_b32 s5, s5, 2
	v_cmp_lt_i32_e32 vcc, v4, v51
	s_add_u32 s14, s70, s5
	s_addc_u32 s15, s71, 0
	v_cndmask_b32_e32 v4, v227, v4, vcc
	v_lshlrev_b32_e32 v8, 5, v45
	v_lshlrev_b32_e32 v140, 2, v4
	global_load_dwordx4 v[28:31], v8, s[14:15] offset:16
	global_load_dwordx4 v[32:35], v8, s[14:15]
	global_load_dwordx4 v[20:23], v8, s[14:15] offset:80
	global_load_dwordx4 v[24:27], v8, s[14:15] offset:64
	global_load_dwordx4 v[12:15], v8, s[14:15] offset:144
	global_load_dwordx4 v[16:19], v8, s[14:15] offset:128
	global_load_dwordx4 v[4:7], v8, s[14:15] offset:208
	s_nop 0
	global_load_dwordx4 v[8:11], v8, s[14:15] offset:192
	buffer_load_dwordx4 v[106:109], v106, s[76:79], 0 offen sc1
	buffer_load_dwordx4 v[110:113], v110, s[76:79], 0 offen sc1
	buffer_load_dwordx4 v[114:117], v114, s[76:79], 0 offen sc1
	buffer_load_dwordx4 v[118:121], v118, s[76:79], 0 offen sc1
	buffer_load_dwordx4 v[122:125], v122, s[76:79], 0 offen sc1
	buffer_load_dwordx4 v[126:129], v126, s[76:79], 0 offen sc1
	buffer_load_dwordx4 v[130:133], v130, s[76:79], 0 offen sc1
	buffer_load_dwordx4 v[134:137], v134, s[76:79], 0 offen sc1
	s_movk_i32 s11, 0x210
	v_mul_lo_u32 v218, v44, s11
	v_mul_lo_u32 v219, v46, s11
	v_mul_lo_u32 v220, v48, s11
	v_mul_lo_u32 v221, v50, s11
	v_readlane_b32 s11, v254, 25
	v_lshl_add_u64 v[206:207], v[40:41], 2, s[20:21]
	v_lshlrev_b32_e32 v193, 2, v45
	v_add_u32_e32 v231, 0, v49
	v_mov_b32_e32 v41, v97
	v_mov_b32_e32 v44, v97
	v_mov_b32_e32 v46, v97
	s_mov_b32 s4, 0
	s_or_b32 s5, s3, 31
	v_mov_b32_e32 v234, 0
	s_waitcnt vmcnt(16)
	ds_write_b128 v101, v[0:3]
	ds_write_b128 v101, v[36:39] offset:1152
	ds_write_b128 v101, v[74:77] offset:2304
	ds_write_b128 v101, v[62:65] offset:3456
	ds_read_b128 v[0:3], v100
	ds_read_b128 v[36:39], v100 offset:32
	ds_read_b128 v[74:77], v100 offset:64
	ds_read_b128 v[62:65], v100 offset:96
	s_waitcnt lgkmcnt(0)
	v_lshlrev_b32_e32 v86, 16, v3
	v_and_b32_e32 v87, 0xffff0000, v3
	v_lshlrev_b32_e32 v92, 16, v1
	s_waitcnt vmcnt(16)
	v_and_b32_e32 v53, 0xffff0000, v65
	v_and_b32_e32 v55, 0xffff0000, v64
	v_lshlrev_b32_e32 v52, 16, v65
	v_lshlrev_b32_e32 v54, 16, v64
	v_mov_b32_e32 v58, v53
	v_mov_b32_e32 v59, v55
	v_mov_b32_e32 v56, v52
	v_mov_b32_e32 v57, v54
	v_pk_mul_f32 v[58:59], v[58:59], v[58:59]
	v_and_b32_e32 v93, 0xffff0000, v1
	v_pk_fma_f32 v[60:61], v[56:57], v[56:57], v[58:59]
	v_and_b32_e32 v57, 0xffff0000, v63
	v_and_b32_e32 v59, 0xffff0000, v62
	v_lshlrev_b32_e32 v56, 16, v63
	v_lshlrev_b32_e32 v58, 16, v62
	v_mov_b32_e32 v64, v57
	v_mov_b32_e32 v65, v59
	v_mov_b32_e32 v62, v56
	v_mov_b32_e32 v63, v58
	v_pk_mul_f32 v[64:65], v[64:65], v[64:65]
	v_lshlrev_b32_e32 v138, 16, v0
	v_pk_fma_f32 v[66:67], v[62:63], v[62:63], v[64:65]
	v_and_b32_e32 v63, 0xffff0000, v77
	v_and_b32_e32 v65, 0xffff0000, v76
	v_lshlrev_b32_e32 v62, 16, v77
	v_lshlrev_b32_e32 v64, 16, v76
	v_mov_b32_e32 v70, v63
	v_mov_b32_e32 v71, v65
	v_mov_b32_e32 v68, v62
	v_mov_b32_e32 v69, v64
	v_pk_mul_f32 v[70:71], v[70:71], v[70:71]
	v_and_b32_e32 v139, 0xffff0000, v0
	v_pk_fma_f32 v[72:73], v[68:69], v[68:69], v[70:71]
	v_and_b32_e32 v69, 0xffff0000, v75
	v_and_b32_e32 v71, 0xffff0000, v74
	v_lshlrev_b32_e32 v68, 16, v75
	v_lshlrev_b32_e32 v70, 16, v74
	v_mov_b32_e32 v76, v69
	v_mov_b32_e32 v77, v71
	v_mov_b32_e32 v74, v68
	v_mov_b32_e32 v75, v70
	v_pk_mul_f32 v[76:77], v[76:77], v[76:77]
	v_and_b32_e32 v79, 0xffff0000, v38
	v_pk_fma_f32 v[76:77], v[74:75], v[74:75], v[76:77]
	v_and_b32_e32 v75, 0xffff0000, v39
	v_pk_mul_f32 v[88:89], v[86:87], v[86:87]
	v_lshlrev_b32_e32 v90, 16, v2
	v_and_b32_e32 v91, 0xffff0000, v2
	v_pk_mul_f32 v[94:95], v[92:93], v[92:93]
	v_pk_mul_f32 v[0:1], v[138:139], v[138:139]
	v_lshlrev_b32_e32 v74, 16, v39
	v_lshlrev_b32_e32 v78, 16, v38
	v_mov_b32_e32 v80, v75
	v_mov_b32_e32 v81, v79
	v_pk_mul_f32 v[2:3], v[90:91], v[90:91]
	v_add_f32_e32 v88, v88, v89
	v_add_f32_e32 v89, v94, v95
	v_add_f32_e32 v0, v0, v1
	v_mov_b32_e32 v38, v74
	v_mov_b32_e32 v39, v78
	v_pk_mul_f32 v[80:81], v[80:81], v[80:81]
	v_lshlrev_b32_e32 v84, 16, v36
	v_and_b32_e32 v85, 0xffff0000, v36
	v_add_f32_e32 v0, v0, v89
	v_add_f32_e32 v1, v2, v3
	v_pk_fma_f32 v[38:39], v[38:39], v[38:39], v[80:81]
	v_lshlrev_b32_e32 v80, 16, v37
	v_and_b32_e32 v81, 0xffff0000, v37
	v_pk_mul_f32 v[36:37], v[84:85], v[84:85]
	v_add_f32_e32 v0, v1, v0
	v_pk_mul_f32 v[82:83], v[80:81], v[80:81]
	v_add_f32_e32 v0, v88, v0
	v_add_f32_e32 v1, v36, v37
	v_add_f32_e32 v0, v1, v0
	v_add_f32_e32 v1, v82, v83
	v_add_f32_e32 v0, v1, v0
	v_add_f32_e32 v0, v39, v0
	v_add_f32_e32 v0, v38, v0
	v_add_f32_e32 v0, v77, v0
	v_add_f32_e32 v0, v76, v0
	v_add_f32_e32 v0, v73, v0
	v_add_f32_e32 v0, v72, v0
	v_add_f32_e32 v0, v67, v0
	v_add_f32_e32 v0, v66, v0
	v_add_f32_e32 v0, v61, v0
	v_add_f32_e32 v0, v60, v0
	ds_bpermute_b32 v1, v140, v0
	v_mov_b32_e32 v36, v97
	v_mov_b32_e32 v37, v97
	v_mov_b32_e32 v38, v97
	v_mov_b32_e32 v39, v97
	s_waitcnt lgkmcnt(0)
	v_add_f32_e32 v0, v0, v1
	v_fmamk_f32 v0, v0, 0x3c800000, v225
	v_cmp_gt_f32_e32 vcc, s30, v0
	v_mul_f32_e32 v1, 0x4b800000, v0
	s_nop 0
	v_cndmask_b32_e32 v0, v0, v1, vcc
	v_rsq_f32_e32 v0, v0
	s_nop 0
	v_mul_f32_e32 v1, 0x45800000, v0
	v_cndmask_b32_e32 v0, v0, v1, vcc
	v_mul_f32_e32 v0, 0x3e38aa3b, v0
	v_pk_mul_f32 v[2:3], v[0:1], v[138:139] op_sel_hi:[0,1]
	s_waitcnt vmcnt(14)
	v_pk_mul_f32 v[2:3], v[32:33], v[2:3]
	v_mov_b32_e32 v32, v97
	v_cvt_pk_bf16_f32 v138, v2, v3
	v_pk_mul_f32 v[2:3], v[0:1], v[92:93] op_sel_hi:[0,1]
	v_pk_mul_f32 v[2:3], v[34:35], v[2:3]
	v_mov_b32_e32 v33, v97
	v_cvt_pk_bf16_f32 v139, v2, v3
	v_pk_mul_f32 v[2:3], v[0:1], v[90:91] op_sel_hi:[0,1]
	v_pk_mul_f32 v[2:3], v[28:29], v[2:3]
	v_mov_b32_e32 v34, v97
	v_cvt_pk_bf16_f32 v140, v2, v3
	v_pk_mul_f32 v[2:3], v[0:1], v[86:87] op_sel_hi:[0,1]
	v_pk_mul_f32 v[2:3], v[30:31], v[2:3]
	v_mov_b32_e32 v35, v97
	v_cvt_pk_bf16_f32 v141, v2, v3
	v_pk_mul_f32 v[2:3], v[0:1], v[84:85] op_sel_hi:[0,1]
	s_waitcnt vmcnt(12)
	v_pk_mul_f32 v[2:3], v[24:25], v[2:3]
	s_nop 0
	v_cvt_pk_bf16_f32 v142, v2, v3
	v_pk_mul_f32 v[2:3], v[0:1], v[80:81] op_sel_hi:[0,1]
	v_pk_mul_f32 v[2:3], v[26:27], v[2:3]
	s_nop 0
	v_cvt_pk_bf16_f32 v143, v2, v3
	v_pk_mul_f32 v[2:3], v[0:1], v[78:79] op_sel_hi:[0,1]
	v_pk_mul_f32 v[2:3], v[20:21], v[2:3]
	s_nop 0
	v_cvt_pk_bf16_f32 v144, v2, v3
	v_pk_mul_f32 v[2:3], v[0:1], v[74:75] op_sel_hi:[0,1]
	v_pk_mul_f32 v[2:3], v[22:23], v[2:3]
	s_nop 0
	v_cvt_pk_bf16_f32 v145, v2, v3
	v_pk_mul_f32 v[2:3], v[0:1], v[70:71] op_sel_hi:[0,1]
	s_waitcnt vmcnt(10)
	v_pk_mul_f32 v[2:3], v[16:17], v[2:3]
	v_xor_b32_e32 v16, 1, v227
	v_cvt_pk_bf16_f32 v146, v2, v3
	v_pk_mul_f32 v[2:3], v[0:1], v[68:69] op_sel_hi:[0,1]
	v_pk_mul_f32 v[2:3], v[18:19], v[2:3]
	v_cmp_lt_i32_e32 vcc, v16, v51
	v_cvt_pk_bf16_f32 v147, v2, v3
	v_pk_mul_f32 v[2:3], v[0:1], v[64:65] op_sel_hi:[0,1]
	v_pk_mul_f32 v[2:3], v[12:13], v[2:3]
	v_cndmask_b32_e32 v16, v227, v16, vcc
	v_cvt_pk_bf16_f32 v148, v2, v3
	v_pk_mul_f32 v[2:3], v[0:1], v[62:63] op_sel_hi:[0,1]
	v_pk_mul_f32 v[2:3], v[14:15], v[2:3]
	v_lshlrev_b32_e32 v191, 2, v16
	v_cvt_pk_bf16_f32 v149, v2, v3
	v_pk_mul_f32 v[2:3], v[0:1], v[58:59] op_sel_hi:[0,1]
	s_waitcnt vmcnt(8)
	v_pk_mul_f32 v[2:3], v[8:9], v[2:3]
	v_xor_b32_e32 v16, 2, v227
	v_cvt_pk_bf16_f32 v150, v2, v3
	v_pk_mul_f32 v[2:3], v[0:1], v[56:57] op_sel_hi:[0,1]
	v_pk_mul_f32 v[2:3], v[10:11], v[2:3]
	v_cmp_lt_i32_e32 vcc, v16, v51
	v_cvt_pk_bf16_f32 v151, v2, v3
	v_pk_mul_f32 v[2:3], v[0:1], v[54:55] op_sel_hi:[0,1]
	v_pk_mul_f32 v[0:1], v[0:1], v[52:53] op_sel_hi:[0,1]
	v_pk_mul_f32 v[0:1], v[6:7], v[0:1]
	v_cndmask_b32_e32 v16, v227, v16, vcc
	v_cvt_pk_bf16_f32 v153, v0, v1
	s_nop 0
	v_mov_b32_e32 v0, v237
	v_lshlrev_b32_e32 v195, 2, v16
	v_xor_b32_e32 v16, 4, v227
	v_cmp_lt_i32_e32 vcc, v16, v51
	v_mov_b32_e32 v17, v97
	v_pk_mul_f32 v[2:3], v[4:5], v[2:3]
	v_cndmask_b32_e32 v16, v227, v16, vcc
	v_lshlrev_b32_e32 v197, 2, v16
	v_lshlrev_b32_e32 v16, 4, v40
	v_and_b32_e32 v199, 0x1f0, v16
	v_lshlrev_b32_e32 v16, 1, v43
	v_lshl_add_u64 v[204:205], s[12:13], 0, v[16:17]
	v_mul_u32_u24_e32 v17, 0x210, v47
	v_lshl_or_b32 v17, v45, 3, v17
	v_mul_u32_u24_e32 v16, 0x90, v47
	v_add_u32_e32 v232, s11, v17
	v_readlane_b32 s11, v254, 26
	v_cvt_pk_bf16_f32 v152, v2, v3
	v_lshlrev_b32_e32 v203, 2, v40
	v_mul_lo_u32 v205, v42, s93
	v_add3_u32 v233, v16, v49, s11
	v_mov_b32_e32 v40, v97
	v_mov_b32_e32 v42, v97
	v_mov_b32_e32 v43, v97
	v_mov_b32_e32 v45, v97
	v_mov_b32_e32 v47, v97
	v_mov_b64_e32 v[16:17], v[32:33]
	s_mov_b64 s[20:21], -1
	v_mov_b64_e32 v[18:19], v[34:35]
	v_mov_b64_e32 v[20:21], v[36:37]
	v_mov_b64_e32 v[22:23], v[38:39]
	v_mov_b64_e32 v[24:25], v[40:41]
	v_mov_b64_e32 v[26:27], v[42:43]
	v_mov_b64_e32 v[28:29], v[44:45]
	v_mov_b64_e32 v[30:31], v[46:47]
	s_waitcnt vmcnt(0)
	v_mov_b32_e32 v14, v0
	v_mov_b32_e32 v15, v0
	v_mov_b32_e32 v1, v0
	v_mov_b32_e32 v2, v0
	v_mov_b32_e32 v3, v0
	v_mov_b32_e32 v4, v0
	v_mov_b32_e32 v5, v0
	v_mov_b32_e32 v6, v0
	v_mov_b32_e32 v7, v0
	v_mov_b32_e32 v8, v0
	v_mov_b32_e32 v9, v0
	v_mov_b32_e32 v10, v0
	v_mov_b32_e32 v11, v0
	v_mov_b32_e32 v12, v0
	v_mov_b32_e32 v13, v0
	v_mov_b64_e32 v[62:63], v[14:15]
	v_mov_b64_e32 v[60:61], v[12:13]
	v_mov_b64_e32 v[58:59], v[10:11]
	v_mov_b64_e32 v[56:57], v[8:9]
	v_mov_b64_e32 v[54:55], v[6:7]
	v_mov_b64_e32 v[52:53], v[4:5]
	v_mov_b64_e32 v[50:51], v[2:3]
	v_mov_b64_e32 v[48:49], v[0:1]
	s_branch .LBB0_148
